# selection phase 1: in-lane 32-bin scan as v_cmp + carry-add count (no VALU->SALU->VALU hops), with DPP lane suffix scan
# speedup vs baseline: 1.0063x; 1.0063x over previous
.LBB0_439:
	s_add_i32 s36, s81, 1
	s_lshr_b32 s36, s36, 1
	v_mov_b32_e32 v0, s81
	v_mov_b32_e32 v1, s36
	s_lshl_b32 s36, s36, 2
	v_or_b32_e32 v160, s38, v185
	v_cndmask_b32_e64 v0, v0, v1, s[40:41]
	v_mov_b32_e32 v1, s36
	v_cmp_lt_i32_e32 vcc, s16, v160
	v_mov_b32_e32 v3, 0
	v_cndmask_b32_e64 v5, v1, 0, s[40:41]
	v_lshlrev_b32_e32 v6, 2, v0
	s_mov_b64 s[42:43], -1
	v_lshlrev_b32_e32 v162, 2, v172
	v_mov_b32_e32 v4, 0
	s_waitcnt lgkmcnt(0)
	s_barrier
	v_readlane_b32 s100, v250, 48
	v_readlane_b32 s101, v250, 49
	v_and_b32_e32 v243, 15, v172
	v_lshrrev_b32_e32 v244, 4, v172
	v_lshlrev_b32_e32 v243, 9, v243
	v_lshl_add_u32 v243, v244, 4, v243
	v_lshl_add_u32 v243, v160, 13, v243
	s_nop 1
	global_load_dwordx4 v[64:67], v243, s[100:101]
	global_load_dwordx4 v[68:71], v243, s[100:101] offset:64
	global_load_dwordx4 v[72:75], v243, s[100:101] offset:128
	global_load_dwordx4 v[76:79], v243, s[100:101] offset:192
	global_load_dwordx4 v[80:83], v243, s[100:101] offset:256
	global_load_dwordx4 v[84:87], v243, s[100:101] offset:320
	global_load_dwordx4 v[88:91], v243, s[100:101] offset:384
	global_load_dwordx4 v[92:95], v243, s[100:101] offset:448
	s_and_saveexec_b64 s[38:39], vcc
	s_cbranch_execz .LBB0_441
	v_lshl_add_u32 v0, v172, 6, v187
	ds_read_b128 v[8:11], v0
	ds_read_b128 v[12:15], v0 offset:16
	s_waitcnt vmcnt(31)
	ds_read_b128 v[16:19], v0 offset:32
	s_waitcnt vmcnt(30)
	ds_read_b128 v[20:23], v0 offset:48
	s_waitcnt vmcnt(10)
	v_add_u32_e32 v35, 4, v162
	s_waitcnt lgkmcnt(3)
	v_add_u32_sdwa v0, v8, v8 dst_sel:DWORD dst_unused:UNUSED_PAD src0_sel:WORD_1 src1_sel:WORD_0
	v_and_b32_e32 v1, 0xffff, v9
	v_lshrrev_b32_e32 v2, 16, v9
	v_add3_u32 v0, v2, v0, v1
	v_and_b32_e32 v4, 0xffff, v10
	v_lshrrev_b32_e32 v7, 16, v10
	v_add3_u32 v0, v7, v0, v4
	v_and_b32_e32 v9, 0xffff, v11
	v_lshrrev_b32_e32 v10, 16, v11
	v_add3_u32 v0, v10, v0, v9
	s_waitcnt lgkmcnt(2)
	v_and_b32_e32 v11, 0xffff, v12
	v_lshrrev_b32_e32 v12, 16, v12
	v_add3_u32 v0, v12, v0, v11
	v_and_b32_e32 v24, 0xffff, v13
	v_lshrrev_b32_e32 v13, 16, v13
	v_add3_u32 v0, v13, v0, v24
	v_and_b32_e32 v25, 0xffff, v14
	v_lshrrev_b32_e32 v14, 16, v14
	v_add3_u32 v0, v14, v0, v25
	v_and_b32_e32 v26, 0xffff, v15
	v_lshrrev_b32_e32 v15, 16, v15
	v_add3_u32 v0, v15, v0, v26
	s_waitcnt lgkmcnt(1)
	v_and_b32_e32 v27, 0xffff, v16
	v_lshrrev_b32_e32 v16, 16, v16
	v_add3_u32 v0, v16, v0, v27
	v_and_b32_e32 v28, 0xffff, v17
	v_lshrrev_b32_e32 v17, 16, v17
	v_add3_u32 v0, v17, v0, v28
	v_and_b32_e32 v29, 0xffff, v18
	v_lshrrev_b32_e32 v18, 16, v18
	v_add3_u32 v0, v18, v0, v29
	v_and_b32_e32 v30, 0xffff, v19
	v_lshrrev_b32_e32 v19, 16, v19
	v_add3_u32 v0, v19, v0, v30
	s_waitcnt lgkmcnt(0)
	v_and_b32_e32 v31, 0xffff, v20
	v_lshrrev_b32_e32 v20, 16, v20
	v_add3_u32 v0, v20, v0, v31
	v_and_b32_e32 v32, 0xffff, v21
	v_lshrrev_b32_e32 v21, 16, v21
	v_add3_u32 v0, v21, v0, v32
	v_and_b32_e32 v33, 0xffff, v22
	v_lshrrev_b32_e32 v22, 16, v22
	v_add3_u32 v0, v22, v0, v33
	v_and_b32_e32 v34, 0xffff, v23
	v_lshrrev_b32_e32 v23, 16, v23
	v_add3_u32 v0, v23, v0, v34
	s_movk_i32 s16, 0x100
	s_movk_i32 s15, 0xff
	v_cmp_ge_u32_e64 s[44:45], v5, v6
	v_mov_b32_e32 v36, v0
	s_nop 1
	v_add_u32_dpp v36, v36, v36 row_shr:1 row_mask:0xf bank_mask:0xf
	s_nop 1
	v_add_u32_dpp v36, v36, v36 row_shr:2 row_mask:0xf bank_mask:0xf
	s_nop 1
	v_add_u32_dpp v36, v36, v36 row_shr:4 row_mask:0xf bank_mask:0xf
	s_nop 1
	v_add_u32_dpp v36, v36, v36 row_shr:8 row_mask:0xf bank_mask:0xf
	s_nop 1
	v_add_u32_dpp v36, v36, v36 row_bcast:15 row_mask:0xa bank_mask:0xf
	s_nop 1
	v_add_u32_dpp v36, v36, v36 row_bcast:31 row_mask:0xc bank_mask:0xf
	s_nop 1
	v_readlane_b32 s36, v36, 63
	s_nop 1
	v_sub_u32_e32 v35, s36, v36
	v_add_u32_e32 v35, v35, v0
	v_sub_u32_e32 v0, v35, v0
	v_cmp_lt_i32_e64 s[46:47], s15, v35
	s_movk_i32 s16, 0xff
	v_mov_b32_e32 v36, 0
	s_bcnt1_i32_b64 s42, s[46:47]
	s_add_i32 s42, s42, -1
	v_add_u32_e32 v0, v23, v0
	v_cmp_lt_i32_e64 s[46:47], s15, v0
	v_add_u32_e32 v0, v34, v0
	v_cmp_lt_i32_e64 s[48:49], s15, v0
	v_addc_co_u32_e64 v36, s[36:37], 0, v36, s[46:47]
	v_add_u32_e32 v0, v22, v0
	v_cmp_lt_i32_e64 s[46:47], s15, v0
	v_addc_co_u32_e64 v36, s[36:37], 0, v36, s[48:49]
	v_add_u32_e32 v0, v33, v0
	v_cmp_lt_i32_e64 s[48:49], s15, v0
	v_addc_co_u32_e64 v36, s[36:37], 0, v36, s[46:47]
	v_add_u32_e32 v0, v21, v0
	v_cmp_lt_i32_e64 s[46:47], s15, v0
	v_addc_co_u32_e64 v36, s[36:37], 0, v36, s[48:49]
	v_add_u32_e32 v0, v32, v0
	v_cmp_lt_i32_e64 s[48:49], s15, v0
	v_addc_co_u32_e64 v36, s[36:37], 0, v36, s[46:47]
	v_add_u32_e32 v0, v20, v0
	v_cmp_lt_i32_e64 s[46:47], s15, v0
	v_addc_co_u32_e64 v36, s[36:37], 0, v36, s[48:49]
	v_add_u32_e32 v0, v31, v0
	v_cmp_lt_i32_e64 s[48:49], s15, v0
	v_addc_co_u32_e64 v36, s[36:37], 0, v36, s[46:47]
	v_add_u32_e32 v0, v19, v0
	v_cmp_lt_i32_e64 s[46:47], s15, v0
	v_addc_co_u32_e64 v36, s[36:37], 0, v36, s[48:49]
	v_add_u32_e32 v0, v30, v0
	v_cmp_lt_i32_e64 s[48:49], s15, v0
	v_addc_co_u32_e64 v36, s[36:37], 0, v36, s[46:47]
	v_add_u32_e32 v0, v18, v0
	v_cmp_lt_i32_e64 s[46:47], s15, v0
	v_addc_co_u32_e64 v36, s[36:37], 0, v36, s[48:49]
	v_add_u32_e32 v0, v29, v0
	v_cmp_lt_i32_e64 s[48:49], s15, v0
	v_addc_co_u32_e64 v36, s[36:37], 0, v36, s[46:47]
	v_add_u32_e32 v0, v17, v0
	v_cmp_lt_i32_e64 s[46:47], s15, v0
	v_addc_co_u32_e64 v36, s[36:37], 0, v36, s[48:49]
	v_add_u32_e32 v0, v28, v0
	v_cmp_lt_i32_e64 s[48:49], s15, v0
	v_addc_co_u32_e64 v36, s[36:37], 0, v36, s[46:47]
	v_add_u32_e32 v0, v16, v0
	v_cmp_lt_i32_e64 s[46:47], s15, v0
	v_addc_co_u32_e64 v36, s[36:37], 0, v36, s[48:49]
	v_add_u32_e32 v0, v27, v0
	v_cmp_lt_i32_e64 s[48:49], s15, v0
	v_addc_co_u32_e64 v36, s[36:37], 0, v36, s[46:47]
	v_add_u32_e32 v0, v15, v0
	v_cmp_lt_i32_e64 s[46:47], s15, v0
	v_addc_co_u32_e64 v36, s[36:37], 0, v36, s[48:49]
	v_add_u32_e32 v0, v26, v0
	v_cmp_lt_i32_e64 s[48:49], s15, v0
	v_addc_co_u32_e64 v36, s[36:37], 0, v36, s[46:47]
	v_add_u32_e32 v0, v14, v0
	v_cmp_lt_i32_e64 s[46:47], s15, v0
	v_addc_co_u32_e64 v36, s[36:37], 0, v36, s[48:49]
	v_add_u32_e32 v0, v25, v0
	v_cmp_lt_i32_e64 s[48:49], s15, v0
	v_addc_co_u32_e64 v36, s[36:37], 0, v36, s[46:47]
	v_add_u32_e32 v0, v13, v0
	v_cmp_lt_i32_e64 s[46:47], s15, v0
	v_addc_co_u32_e64 v36, s[36:37], 0, v36, s[48:49]
	v_add_u32_e32 v0, v24, v0
	v_cmp_lt_i32_e64 s[48:49], s15, v0
	v_addc_co_u32_e64 v36, s[36:37], 0, v36, s[46:47]
	v_add_u32_e32 v0, v12, v0
	v_cmp_lt_i32_e64 s[46:47], s15, v0
	v_addc_co_u32_e64 v36, s[36:37], 0, v36, s[48:49]
	v_add_u32_e32 v0, v11, v0
	v_cmp_lt_i32_e64 s[48:49], s15, v0
	v_addc_co_u32_e64 v36, s[36:37], 0, v36, s[46:47]
	v_add_u32_e32 v0, v10, v0
	v_cmp_lt_i32_e64 s[46:47], s15, v0
	v_addc_co_u32_e64 v36, s[36:37], 0, v36, s[48:49]
	v_add_u32_e32 v0, v9, v0
	v_cmp_lt_i32_e64 s[48:49], s15, v0
	v_addc_co_u32_e64 v36, s[36:37], 0, v36, s[46:47]
	v_add_u32_e32 v0, v7, v0
	v_cmp_lt_i32_e64 s[46:47], s15, v0
	v_addc_co_u32_e64 v36, s[36:37], 0, v36, s[48:49]
	v_add_u32_e32 v0, v4, v0
	v_cmp_lt_i32_e64 s[48:49], s15, v0
	v_addc_co_u32_e64 v36, s[36:37], 0, v36, s[46:47]
	v_add_u32_e32 v0, v2, v0
	v_cmp_lt_i32_e64 s[46:47], s15, v0
	v_addc_co_u32_e64 v36, s[36:37], 0, v36, s[48:49]
	v_add_u32_e32 v0, v1, v0
	v_cmp_lt_i32_e64 s[48:49], s15, v0
	v_addc_co_u32_e64 v36, s[36:37], 0, v36, s[46:47]
	v_add_u32_sdwa v0, v8, v0 dst_sel:DWORD dst_unused:UNUSED_PAD src0_sel:WORD_1 src1_sel:DWORD
	s_nop 0
	v_cmp_lt_i32_e64 s[46:47], s15, v0
	v_addc_co_u32_e64 v36, s[36:37], 0, v36, s[48:49]
	v_add_u32_sdwa v0, v8, v0 dst_sel:DWORD dst_unused:UNUSED_PAD src0_sel:WORD_0 src1_sel:DWORD
	s_nop 0
	v_cmp_lt_i32_e64 s[48:49], s15, v0
	v_addc_co_u32_e64 v36, s[36:37], 0, v36, s[46:47]
	s_nop 1
	v_addc_co_u32_e64 v36, s[36:37], 0, v36, s[48:49]
	s_lshl_b32 s37, s42, 26
	v_add_u32_e32 v0, -1, v36
	s_nop 1
	v_readlane_b32 s36, v0, s42
	s_lshl_b32 s36, s36, 21
	s_add_i32 s36, s36, s37
	v_mov_b32_e32 v4, s36
	s_orn2_b64 s[42:43], s[44:45], exec
